# M_GATE sigmoid: 8 redundant bias v_movs per fragment removed (adds read the hoisted bias registers directly); otherwise v136
# baseline (speedup 1.0000x reference)
.LBB0_251:
	s_and_b64 vcc, exec, s[50:51]
	s_cbranch_vccz .LBB0_253
	v_add_u32_e32 v150, s10, v146
	v_ashrrev_i32_e32 v151, 31, v150
	v_lshl_add_u64 v[126:127], v[150:151], 2, s[98:99]
	global_load_dwordx4 v[228:231], v[126:127], off
	global_load_dwordx4 v[232:235], v[126:127], off offset:16
	s_waitcnt vmcnt(0)
	v_add_f32_e32 v122, v176, v228
	v_add_f32_e32 v126, v188, v232
	v_add_f32_e32 v123, v177, v229
	v_add_f32_e32 v127, v189, v233
	v_add_f32_e32 v124, v172, v230
	v_add_f32_e32 v128, v186, v234
	v_add_f32_e32 v125, v173, v231
	v_add_f32_e32 v129, v187, v235
	v_mul_f32_e32 v122, 0xbfb8aa3b, v122
	v_mul_f32_e32 v126, 0xbfb8aa3b, v126
	v_mul_f32_e32 v123, 0xbfb8aa3b, v123
	v_mul_f32_e32 v127, 0xbfb8aa3b, v127
	v_mul_f32_e32 v124, 0xbfb8aa3b, v124
	v_mul_f32_e32 v128, 0xbfb8aa3b, v128
	v_mul_f32_e32 v125, 0xbfb8aa3b, v125
	v_mul_f32_e32 v129, 0xbfb8aa3b, v129
	v_exp_f32_e32 v122, v122
	v_exp_f32_e32 v126, v126
	v_exp_f32_e32 v123, v123
	v_exp_f32_e32 v127, v127
	v_exp_f32_e32 v124, v124
	v_exp_f32_e32 v128, v128
	v_exp_f32_e32 v125, v125
	v_exp_f32_e32 v129, v129
	v_add_f32_e32 v122, 1.0, v122
	v_add_f32_e32 v126, 1.0, v126
	v_add_f32_e32 v123, 1.0, v123
	v_add_f32_e32 v127, 1.0, v127
	v_add_f32_e32 v124, 1.0, v124
	v_add_f32_e32 v128, 1.0, v128
	v_add_f32_e32 v125, 1.0, v125
	v_add_f32_e32 v129, 1.0, v129
	v_rcp_f32_e32 v122, v122
	v_rcp_f32_e32 v126, v126
	v_rcp_f32_e32 v123, v123
	v_rcp_f32_e32 v127, v127
	v_rcp_f32_e32 v124, v124
	v_rcp_f32_e32 v128, v128
	v_rcp_f32_e32 v125, v125
	v_rcp_f32_e32 v129, v129
	v_mul_f32_e32 v122, 0x437f0000, v122
	v_mul_f32_e32 v126, 0x437f0000, v126
	v_mul_f32_e32 v123, 0x437f0000, v123
	v_mul_f32_e32 v127, 0x437f0000, v127
	v_mul_f32_e32 v124, 0x437f0000, v124
	v_mul_f32_e32 v128, 0x437f0000, v128
	v_mul_f32_e32 v125, 0x437f0000, v125
	v_mul_f32_e32 v129, 0x437f0000, v129
	v_rndne_f32_e32 v122, v122
	v_rndne_f32_e32 v126, v126
	v_rndne_f32_e32 v123, v123
	v_rndne_f32_e32 v127, v127
	v_rndne_f32_e32 v124, v124
	v_rndne_f32_e32 v128, v128
	v_rndne_f32_e32 v125, v125
	v_rndne_f32_e32 v129, v129
	v_cvt_u32_f32_e32 v122, v122
	v_cvt_u32_f32_e32 v126, v126
	v_cvt_u32_f32_e32 v123, v123
	v_cvt_u32_f32_e32 v127, v127
	v_cvt_u32_f32_sdwa v124, v124 dst_sel:WORD_1 dst_unused:UNUSED_PAD src0_sel:DWORD
	v_cvt_u32_f32_sdwa v128, v128 dst_sel:WORD_1 dst_unused:UNUSED_PAD src0_sel:DWORD
	v_cvt_u32_f32_sdwa v125, v125 dst_sel:BYTE_3 dst_unused:UNUSED_PAD src0_sel:DWORD
	v_cvt_u32_f32_sdwa v129, v129 dst_sel:BYTE_3 dst_unused:UNUSED_PAD src0_sel:DWORD
	v_lshl_or_b32 v122, v123, 8, v122
	v_lshl_or_b32 v123, v127, 8, v126
	v_or3_b32 v122, v122, v124, v125
	v_or3_b32 v123, v123, v128, v129
	v_lshl_add_u64 v[124:125], v[162:163], 0, v[150:151]
	global_store_dwordx2 v[124:125], v[122:123], off

.LBB0_308:
	s_and_b64 vcc, exec, s[50:51]
	s_cbranch_vccz .LBB0_310
	v_add_u32_e32 v168, s10, v122
	v_ashrrev_i32_e32 v169, 31, v168
	v_lshl_add_u64 v[118:119], v[168:169], 2, s[98:99]
	global_load_dwordx4 v[236:239], v[118:119], off
	global_load_dwordx2 v[240:241], v[118:119], off offset:16
	global_load_dwordx2 v[206:207], v[118:119], off offset:24
	s_waitcnt vmcnt(0)
	v_add_f32_e32 v114, v172, v236
	v_add_f32_e32 v118, v178, v240
	v_add_f32_e32 v115, v173, v237
	v_add_f32_e32 v119, v179, v241
	v_add_f32_e32 v116, v124, v238
	v_add_f32_e32 v120, v176, v206
	v_add_f32_e32 v117, v125, v239
	v_add_f32_e32 v121, v177, v207
	v_mul_f32_e32 v114, 0xbfb8aa3b, v114
	v_mul_f32_e32 v118, 0xbfb8aa3b, v118
	v_mul_f32_e32 v115, 0xbfb8aa3b, v115
	v_mul_f32_e32 v119, 0xbfb8aa3b, v119
	v_mul_f32_e32 v116, 0xbfb8aa3b, v116
	v_mul_f32_e32 v120, 0xbfb8aa3b, v120
	v_mul_f32_e32 v117, 0xbfb8aa3b, v117
	v_mul_f32_e32 v121, 0xbfb8aa3b, v121
	v_exp_f32_e32 v114, v114
	v_exp_f32_e32 v118, v118
	v_exp_f32_e32 v115, v115
	v_exp_f32_e32 v119, v119
	v_exp_f32_e32 v116, v116
	v_exp_f32_e32 v120, v120
	v_exp_f32_e32 v117, v117
	v_exp_f32_e32 v121, v121
	v_add_f32_e32 v114, 1.0, v114
	v_add_f32_e32 v118, 1.0, v118
	v_add_f32_e32 v115, 1.0, v115
	v_add_f32_e32 v119, 1.0, v119
	v_add_f32_e32 v116, 1.0, v116
	v_add_f32_e32 v120, 1.0, v120
	v_add_f32_e32 v117, 1.0, v117
	v_add_f32_e32 v121, 1.0, v121
	v_rcp_f32_e32 v114, v114
	v_rcp_f32_e32 v118, v118
	v_rcp_f32_e32 v115, v115
	v_rcp_f32_e32 v119, v119
	v_rcp_f32_e32 v116, v116
	v_rcp_f32_e32 v120, v120
	v_rcp_f32_e32 v117, v117
	v_rcp_f32_e32 v121, v121
	v_mul_f32_e32 v114, 0x437f0000, v114
	v_mul_f32_e32 v118, 0x437f0000, v118
	v_mul_f32_e32 v115, 0x437f0000, v115
	v_mul_f32_e32 v119, 0x437f0000, v119
	v_mul_f32_e32 v116, 0x437f0000, v116
	v_mul_f32_e32 v120, 0x437f0000, v120
	v_mul_f32_e32 v117, 0x437f0000, v117
	v_mul_f32_e32 v121, 0x437f0000, v121
	v_rndne_f32_e32 v114, v114
	v_rndne_f32_e32 v118, v118
	v_rndne_f32_e32 v115, v115
	v_rndne_f32_e32 v119, v119
	v_rndne_f32_e32 v116, v116
	v_rndne_f32_e32 v120, v120
	v_rndne_f32_e32 v117, v117
	v_rndne_f32_e32 v121, v121
	v_cvt_u32_f32_e32 v114, v114
	v_cvt_u32_f32_e32 v118, v118
	v_cvt_u32_f32_e32 v115, v115
	v_cvt_u32_f32_e32 v119, v119
	v_cvt_u32_f32_sdwa v116, v116 dst_sel:WORD_1 dst_unused:UNUSED_PAD src0_sel:DWORD
	v_cvt_u32_f32_sdwa v120, v120 dst_sel:WORD_1 dst_unused:UNUSED_PAD src0_sel:DWORD
	v_cvt_u32_f32_sdwa v117, v117 dst_sel:BYTE_3 dst_unused:UNUSED_PAD src0_sel:DWORD
	v_cvt_u32_f32_sdwa v121, v121 dst_sel:BYTE_3 dst_unused:UNUSED_PAD src0_sel:DWORD
	v_lshl_or_b32 v114, v115, 8, v114
	v_lshl_or_b32 v115, v119, 8, v118
	v_or3_b32 v114, v114, v116, v117
	v_or3_b32 v115, v115, v120, v121
	v_lshl_add_u64 v[116:117], v[162:163], 0, v[168:169]
	global_store_dwordx2 v[116:117], v[114:115], off

.LBB0_381:
	s_and_b64 vcc, exec, s[50:51]
	s_cbranch_vccz .LBB0_383
	v_add_u32_e32 v120, s10, v146
	v_ashrrev_i32_e32 v121, 31, v120
	v_add_f32_e32 v106, v174, v228
	v_add_f32_e32 v110, v178, v232
	v_add_f32_e32 v107, v175, v229
	v_add_f32_e32 v111, v179, v233
	v_add_f32_e32 v108, v162, v230
	v_add_f32_e32 v112, v176, v234
	v_add_f32_e32 v109, v163, v231
	v_add_f32_e32 v113, v177, v235
	v_mul_f32_e32 v106, 0xbfb8aa3b, v106
	v_mul_f32_e32 v110, 0xbfb8aa3b, v110
	v_mul_f32_e32 v107, 0xbfb8aa3b, v107
	v_mul_f32_e32 v111, 0xbfb8aa3b, v111
	v_mul_f32_e32 v108, 0xbfb8aa3b, v108
	v_mul_f32_e32 v112, 0xbfb8aa3b, v112
	v_mul_f32_e32 v109, 0xbfb8aa3b, v109
	v_mul_f32_e32 v113, 0xbfb8aa3b, v113
	v_exp_f32_e32 v106, v106
	v_exp_f32_e32 v110, v110
	v_exp_f32_e32 v107, v107
	v_exp_f32_e32 v111, v111
	v_exp_f32_e32 v108, v108
	v_exp_f32_e32 v112, v112
	v_exp_f32_e32 v109, v109
	v_exp_f32_e32 v113, v113
	v_add_f32_e32 v106, 1.0, v106
	v_add_f32_e32 v110, 1.0, v110
	v_add_f32_e32 v107, 1.0, v107
	v_add_f32_e32 v111, 1.0, v111
	v_add_f32_e32 v108, 1.0, v108
	v_add_f32_e32 v112, 1.0, v112
	v_add_f32_e32 v109, 1.0, v109
	v_add_f32_e32 v113, 1.0, v113
	v_rcp_f32_e32 v106, v106
	v_rcp_f32_e32 v110, v110
	v_rcp_f32_e32 v107, v107
	v_rcp_f32_e32 v111, v111
	v_rcp_f32_e32 v108, v108
	v_rcp_f32_e32 v112, v112
	v_rcp_f32_e32 v109, v109
	v_rcp_f32_e32 v113, v113
	v_mul_f32_e32 v106, 0x437f0000, v106
	v_mul_f32_e32 v110, 0x437f0000, v110
	v_mul_f32_e32 v107, 0x437f0000, v107
	v_mul_f32_e32 v111, 0x437f0000, v111
	v_mul_f32_e32 v108, 0x437f0000, v108
	v_mul_f32_e32 v112, 0x437f0000, v112
	v_mul_f32_e32 v109, 0x437f0000, v109
	v_mul_f32_e32 v113, 0x437f0000, v113
	v_rndne_f32_e32 v106, v106
	v_rndne_f32_e32 v110, v110
	v_rndne_f32_e32 v107, v107
	v_rndne_f32_e32 v111, v111
	v_rndne_f32_e32 v108, v108
	v_rndne_f32_e32 v112, v112
	v_rndne_f32_e32 v109, v109
	v_rndne_f32_e32 v113, v113
	v_cvt_u32_f32_e32 v106, v106
	v_cvt_u32_f32_e32 v110, v110
	v_cvt_u32_f32_e32 v107, v107
	v_cvt_u32_f32_e32 v111, v111
	v_cvt_u32_f32_sdwa v108, v108 dst_sel:WORD_1 dst_unused:UNUSED_PAD src0_sel:DWORD
	v_cvt_u32_f32_sdwa v112, v112 dst_sel:WORD_1 dst_unused:UNUSED_PAD src0_sel:DWORD
	v_cvt_u32_f32_sdwa v109, v109 dst_sel:BYTE_3 dst_unused:UNUSED_PAD src0_sel:DWORD
	v_cvt_u32_f32_sdwa v113, v113 dst_sel:BYTE_3 dst_unused:UNUSED_PAD src0_sel:DWORD
	v_lshl_or_b32 v106, v107, 8, v106
	v_lshl_or_b32 v107, v111, 8, v110
	v_or3_b32 v106, v106, v108, v109
	v_or3_b32 v107, v107, v112, v113
	v_lshl_add_u64 v[108:109], v[152:153], 0, v[120:121]
	global_store_dwordx2 v[108:109], v[106:107], off

.LBB0_440:
	s_and_b64 vcc, exec, s[50:51]
	s_cbranch_vccz .LBB0_442
	v_add_u32_e32 v158, s10, v122
	v_ashrrev_i32_e32 v159, 31, v158
	v_add_f32_e32 v98, v108, v236
	v_add_f32_e32 v102, v164, v240
	v_add_f32_e32 v99, v109, v237
	v_add_f32_e32 v103, v165, v241
	v_add_f32_e32 v100, v106, v238
	v_add_f32_e32 v104, v162, v206
	v_add_f32_e32 v101, v107, v239
	v_add_f32_e32 v105, v163, v207
	v_mul_f32_e32 v98, 0xbfb8aa3b, v98
	v_mul_f32_e32 v102, 0xbfb8aa3b, v102
	v_mul_f32_e32 v99, 0xbfb8aa3b, v99
	v_mul_f32_e32 v103, 0xbfb8aa3b, v103
	v_mul_f32_e32 v100, 0xbfb8aa3b, v100
	v_mul_f32_e32 v104, 0xbfb8aa3b, v104
	v_mul_f32_e32 v101, 0xbfb8aa3b, v101
	v_mul_f32_e32 v105, 0xbfb8aa3b, v105
	v_exp_f32_e32 v98, v98
	v_exp_f32_e32 v102, v102
	v_exp_f32_e32 v99, v99
	v_exp_f32_e32 v103, v103
	v_exp_f32_e32 v100, v100
	v_exp_f32_e32 v104, v104
	v_exp_f32_e32 v101, v101
	v_exp_f32_e32 v105, v105
	v_add_f32_e32 v98, 1.0, v98
	v_add_f32_e32 v102, 1.0, v102
	v_add_f32_e32 v99, 1.0, v99
	v_add_f32_e32 v103, 1.0, v103
	v_add_f32_e32 v100, 1.0, v100
	v_add_f32_e32 v104, 1.0, v104
	v_add_f32_e32 v101, 1.0, v101
	v_add_f32_e32 v105, 1.0, v105
	v_rcp_f32_e32 v98, v98
	v_rcp_f32_e32 v102, v102
	v_rcp_f32_e32 v99, v99
	v_rcp_f32_e32 v103, v103
	v_rcp_f32_e32 v100, v100
	v_rcp_f32_e32 v104, v104
	v_rcp_f32_e32 v101, v101
	v_rcp_f32_e32 v105, v105
	v_mul_f32_e32 v98, 0x437f0000, v98
	v_mul_f32_e32 v102, 0x437f0000, v102
	v_mul_f32_e32 v99, 0x437f0000, v99
	v_mul_f32_e32 v103, 0x437f0000, v103
	v_mul_f32_e32 v100, 0x437f0000, v100
	v_mul_f32_e32 v104, 0x437f0000, v104
	v_mul_f32_e32 v101, 0x437f0000, v101
	v_mul_f32_e32 v105, 0x437f0000, v105
	v_rndne_f32_e32 v98, v98
	v_rndne_f32_e32 v102, v102
	v_rndne_f32_e32 v99, v99
	v_rndne_f32_e32 v103, v103
	v_rndne_f32_e32 v100, v100
	v_rndne_f32_e32 v104, v104
	v_rndne_f32_e32 v101, v101
	v_rndne_f32_e32 v105, v105
	v_cvt_u32_f32_e32 v98, v98
	v_cvt_u32_f32_e32 v102, v102
	v_cvt_u32_f32_e32 v99, v99
	v_cvt_u32_f32_e32 v103, v103
	v_cvt_u32_f32_sdwa v100, v100 dst_sel:WORD_1 dst_unused:UNUSED_PAD src0_sel:DWORD
	v_cvt_u32_f32_sdwa v104, v104 dst_sel:WORD_1 dst_unused:UNUSED_PAD src0_sel:DWORD
	v_cvt_u32_f32_sdwa v101, v101 dst_sel:BYTE_3 dst_unused:UNUSED_PAD src0_sel:DWORD
	v_cvt_u32_f32_sdwa v105, v105 dst_sel:BYTE_3 dst_unused:UNUSED_PAD src0_sel:DWORD
	v_lshl_or_b32 v98, v99, 8, v98
	v_lshl_or_b32 v99, v103, 8, v102
	v_or3_b32 v98, v98, v100, v101
	v_or3_b32 v99, v99, v104, v105
	v_lshl_add_u64 v[100:101], v[152:153], 0, v[158:159]
	global_store_dwordx2 v[100:101], v[98:99], off

.LBB0_508:
	s_and_b64 vcc, exec, s[50:51]
	s_cbranch_vccz .LBB0_510
	v_add_u32_e32 v102, s10, v146
	v_ashrrev_i32_e32 v103, 31, v102
	v_add_f32_e32 v90, v158, v228
	v_add_f32_e32 v94, v162, v232
	v_add_f32_e32 v91, v159, v229
	v_add_f32_e32 v95, v163, v233
	v_add_f32_e32 v92, v120, v230
	v_add_f32_e32 v96, v160, v234
	v_add_f32_e32 v93, v121, v231
	v_add_f32_e32 v97, v161, v235
	v_mul_f32_e32 v90, 0xbfb8aa3b, v90
	v_mul_f32_e32 v94, 0xbfb8aa3b, v94
	v_mul_f32_e32 v91, 0xbfb8aa3b, v91
	v_mul_f32_e32 v95, 0xbfb8aa3b, v95
	v_mul_f32_e32 v92, 0xbfb8aa3b, v92
	v_mul_f32_e32 v96, 0xbfb8aa3b, v96
	v_mul_f32_e32 v93, 0xbfb8aa3b, v93
	v_mul_f32_e32 v97, 0xbfb8aa3b, v97
	v_exp_f32_e32 v90, v90
	v_exp_f32_e32 v94, v94
	v_exp_f32_e32 v91, v91
	v_exp_f32_e32 v95, v95
	v_exp_f32_e32 v92, v92
	v_exp_f32_e32 v96, v96
	v_exp_f32_e32 v93, v93
	v_exp_f32_e32 v97, v97
	v_add_f32_e32 v90, 1.0, v90
	v_add_f32_e32 v94, 1.0, v94
	v_add_f32_e32 v91, 1.0, v91
	v_add_f32_e32 v95, 1.0, v95
	v_add_f32_e32 v92, 1.0, v92
	v_add_f32_e32 v96, 1.0, v96
	v_add_f32_e32 v93, 1.0, v93
	v_add_f32_e32 v97, 1.0, v97
	v_rcp_f32_e32 v90, v90
	v_rcp_f32_e32 v94, v94
	v_rcp_f32_e32 v91, v91
	v_rcp_f32_e32 v95, v95
	v_rcp_f32_e32 v92, v92
	v_rcp_f32_e32 v96, v96
	v_rcp_f32_e32 v93, v93
	v_rcp_f32_e32 v97, v97
	v_mul_f32_e32 v90, 0x437f0000, v90
	v_mul_f32_e32 v94, 0x437f0000, v94
	v_mul_f32_e32 v91, 0x437f0000, v91
	v_mul_f32_e32 v95, 0x437f0000, v95
	v_mul_f32_e32 v92, 0x437f0000, v92
	v_mul_f32_e32 v96, 0x437f0000, v96
	v_mul_f32_e32 v93, 0x437f0000, v93
	v_mul_f32_e32 v97, 0x437f0000, v97
	v_rndne_f32_e32 v90, v90
	v_rndne_f32_e32 v94, v94
	v_rndne_f32_e32 v91, v91
	v_rndne_f32_e32 v95, v95
	v_rndne_f32_e32 v92, v92
	v_rndne_f32_e32 v96, v96
	v_rndne_f32_e32 v93, v93
	v_rndne_f32_e32 v97, v97
	v_cvt_u32_f32_e32 v90, v90
	v_cvt_u32_f32_e32 v94, v94
	v_cvt_u32_f32_e32 v91, v91
	v_cvt_u32_f32_e32 v95, v95
	v_cvt_u32_f32_sdwa v92, v92 dst_sel:WORD_1 dst_unused:UNUSED_PAD src0_sel:DWORD
	v_cvt_u32_f32_sdwa v96, v96 dst_sel:WORD_1 dst_unused:UNUSED_PAD src0_sel:DWORD
	v_cvt_u32_f32_sdwa v93, v93 dst_sel:BYTE_3 dst_unused:UNUSED_PAD src0_sel:DWORD
	v_cvt_u32_f32_sdwa v97, v97 dst_sel:BYTE_3 dst_unused:UNUSED_PAD src0_sel:DWORD
	v_lshl_or_b32 v90, v91, 8, v90
	v_lshl_or_b32 v91, v95, 8, v94
	v_or3_b32 v90, v90, v92, v93
	v_or3_b32 v91, v91, v96, v97
	v_lshl_add_u64 v[92:93], v[108:109], 0, v[102:103]
	global_store_dwordx2 v[92:93], v[90:91], off

.LBB0_570:
	s_and_b64 vcc, exec, s[50:51]
	s_cbranch_vccz .LBB0_572
	v_add_u32_e32 v116, s10, v122
	v_ashrrev_i32_e32 v117, 31, v116
	v_add_f32_e32 v82, v92, v236
	v_add_f32_e32 v86, v124, v240
	v_add_f32_e32 v83, v93, v237
	v_add_f32_e32 v87, v125, v241
	v_add_f32_e32 v84, v90, v238
	v_add_f32_e32 v88, v120, v206
	v_add_f32_e32 v85, v91, v239
	v_add_f32_e32 v89, v121, v207
	v_mul_f32_e32 v82, 0xbfb8aa3b, v82
	v_mul_f32_e32 v86, 0xbfb8aa3b, v86
	v_mul_f32_e32 v83, 0xbfb8aa3b, v83
	v_mul_f32_e32 v87, 0xbfb8aa3b, v87
	v_mul_f32_e32 v84, 0xbfb8aa3b, v84
	v_mul_f32_e32 v88, 0xbfb8aa3b, v88
	v_mul_f32_e32 v85, 0xbfb8aa3b, v85
	v_mul_f32_e32 v89, 0xbfb8aa3b, v89
	v_exp_f32_e32 v82, v82
	v_exp_f32_e32 v86, v86
	v_exp_f32_e32 v83, v83
	v_exp_f32_e32 v87, v87
	v_exp_f32_e32 v84, v84
	v_exp_f32_e32 v88, v88
	v_exp_f32_e32 v85, v85
	v_exp_f32_e32 v89, v89
	v_add_f32_e32 v82, 1.0, v82
	v_add_f32_e32 v86, 1.0, v86
	v_add_f32_e32 v83, 1.0, v83
	v_add_f32_e32 v87, 1.0, v87
	v_add_f32_e32 v84, 1.0, v84
	v_add_f32_e32 v88, 1.0, v88
	v_add_f32_e32 v85, 1.0, v85
	v_add_f32_e32 v89, 1.0, v89
	v_rcp_f32_e32 v82, v82
	v_rcp_f32_e32 v86, v86
	v_rcp_f32_e32 v83, v83
	v_rcp_f32_e32 v87, v87
	v_rcp_f32_e32 v84, v84
	v_rcp_f32_e32 v88, v88
	v_rcp_f32_e32 v85, v85
	v_rcp_f32_e32 v89, v89
	v_mul_f32_e32 v82, 0x437f0000, v82
	v_mul_f32_e32 v86, 0x437f0000, v86
	v_mul_f32_e32 v83, 0x437f0000, v83
	v_mul_f32_e32 v87, 0x437f0000, v87
	v_mul_f32_e32 v84, 0x437f0000, v84
	v_mul_f32_e32 v88, 0x437f0000, v88
	v_mul_f32_e32 v85, 0x437f0000, v85
	v_mul_f32_e32 v89, 0x437f0000, v89
	v_rndne_f32_e32 v82, v82
	v_rndne_f32_e32 v86, v86
	v_rndne_f32_e32 v83, v83
	v_rndne_f32_e32 v87, v87
	v_rndne_f32_e32 v84, v84
	v_rndne_f32_e32 v88, v88
	v_rndne_f32_e32 v85, v85
	v_rndne_f32_e32 v89, v89
	v_cvt_u32_f32_e32 v82, v82
	v_cvt_u32_f32_e32 v86, v86
	v_cvt_u32_f32_e32 v83, v83
	v_cvt_u32_f32_e32 v87, v87
	v_cvt_u32_f32_sdwa v84, v84 dst_sel:WORD_1 dst_unused:UNUSED_PAD src0_sel:DWORD
	v_cvt_u32_f32_sdwa v88, v88 dst_sel:WORD_1 dst_unused:UNUSED_PAD src0_sel:DWORD
	v_cvt_u32_f32_sdwa v85, v85 dst_sel:BYTE_3 dst_unused:UNUSED_PAD src0_sel:DWORD
	v_cvt_u32_f32_sdwa v89, v89 dst_sel:BYTE_3 dst_unused:UNUSED_PAD src0_sel:DWORD
	v_lshl_or_b32 v82, v83, 8, v82
	v_lshl_or_b32 v83, v87, 8, v86
	v_or3_b32 v82, v82, v84, v85
	v_or3_b32 v83, v83, v88, v89
	v_lshl_add_u64 v[84:85], v[108:109], 0, v[116:117]
	global_store_dwordx2 v[84:85], v[82:83], off

.LBB0_638:
	s_and_b64 vcc, exec, s[50:51]
	s_cbranch_vccz .LBB0_640
	v_add_u32_e32 v86, s10, v146
	v_ashrrev_i32_e32 v87, 31, v86
	v_add_f32_e32 v74, v116, v228
	v_add_f32_e32 v78, v120, v232
	v_add_f32_e32 v75, v117, v229
	v_add_f32_e32 v79, v121, v233
	v_add_f32_e32 v76, v102, v230
	v_add_f32_e32 v80, v118, v234
	v_add_f32_e32 v77, v103, v231
	v_add_f32_e32 v81, v119, v235
	v_mul_f32_e32 v74, 0xbfb8aa3b, v74
	v_mul_f32_e32 v78, 0xbfb8aa3b, v78
	v_mul_f32_e32 v75, 0xbfb8aa3b, v75
	v_mul_f32_e32 v79, 0xbfb8aa3b, v79
	v_mul_f32_e32 v76, 0xbfb8aa3b, v76
	v_mul_f32_e32 v80, 0xbfb8aa3b, v80
	v_mul_f32_e32 v77, 0xbfb8aa3b, v77
	v_mul_f32_e32 v81, 0xbfb8aa3b, v81
	v_exp_f32_e32 v74, v74
	v_exp_f32_e32 v78, v78
	v_exp_f32_e32 v75, v75
	v_exp_f32_e32 v79, v79
	v_exp_f32_e32 v76, v76
	v_exp_f32_e32 v80, v80
	v_exp_f32_e32 v77, v77
	v_exp_f32_e32 v81, v81
	v_add_f32_e32 v74, 1.0, v74
	v_add_f32_e32 v78, 1.0, v78
	v_add_f32_e32 v75, 1.0, v75
	v_add_f32_e32 v79, 1.0, v79
	v_add_f32_e32 v76, 1.0, v76
	v_add_f32_e32 v80, 1.0, v80
	v_add_f32_e32 v77, 1.0, v77
	v_add_f32_e32 v81, 1.0, v81
	v_rcp_f32_e32 v74, v74
	v_rcp_f32_e32 v78, v78
	v_rcp_f32_e32 v75, v75
	v_rcp_f32_e32 v79, v79
	v_rcp_f32_e32 v76, v76
	v_rcp_f32_e32 v80, v80
	v_rcp_f32_e32 v77, v77
	v_rcp_f32_e32 v81, v81
	v_mul_f32_e32 v74, 0x437f0000, v74
	v_mul_f32_e32 v78, 0x437f0000, v78
	v_mul_f32_e32 v75, 0x437f0000, v75
	v_mul_f32_e32 v79, 0x437f0000, v79
	v_mul_f32_e32 v76, 0x437f0000, v76
	v_mul_f32_e32 v80, 0x437f0000, v80
	v_mul_f32_e32 v77, 0x437f0000, v77
	v_mul_f32_e32 v81, 0x437f0000, v81
	v_rndne_f32_e32 v74, v74
	v_rndne_f32_e32 v78, v78
	v_rndne_f32_e32 v75, v75
	v_rndne_f32_e32 v79, v79
	v_rndne_f32_e32 v76, v76
	v_rndne_f32_e32 v80, v80
	v_rndne_f32_e32 v77, v77
	v_rndne_f32_e32 v81, v81
	v_cvt_u32_f32_e32 v74, v74
	v_cvt_u32_f32_e32 v78, v78
	v_cvt_u32_f32_e32 v75, v75
	v_cvt_u32_f32_e32 v79, v79
	v_cvt_u32_f32_sdwa v76, v76 dst_sel:WORD_1 dst_unused:UNUSED_PAD src0_sel:DWORD
	v_cvt_u32_f32_sdwa v80, v80 dst_sel:WORD_1 dst_unused:UNUSED_PAD src0_sel:DWORD
	v_cvt_u32_f32_sdwa v77, v77 dst_sel:BYTE_3 dst_unused:UNUSED_PAD src0_sel:DWORD
	v_cvt_u32_f32_sdwa v81, v81 dst_sel:BYTE_3 dst_unused:UNUSED_PAD src0_sel:DWORD
	v_lshl_or_b32 v74, v75, 8, v74
	v_lshl_or_b32 v75, v79, 8, v78
	v_or3_b32 v74, v74, v76, v77
	v_or3_b32 v75, v75, v80, v81
	v_lshl_add_u64 v[76:77], v[92:93], 0, v[86:87]
	global_store_dwordx2 v[76:77], v[74:75], off

.LBB0_700:
	s_and_b64 vcc, exec, s[50:51]
	s_cbranch_vccz .LBB0_702
	v_add_u32_e32 v98, s10, v122
	v_ashrrev_i32_e32 v99, 31, v98
	v_add_f32_e32 v66, v76, v236
	v_add_f32_e32 v70, v104, v240
	v_add_f32_e32 v67, v77, v237
	v_add_f32_e32 v71, v105, v241
	v_add_f32_e32 v68, v74, v238
	v_add_f32_e32 v72, v102, v206
	v_add_f32_e32 v69, v75, v239
	v_add_f32_e32 v73, v103, v207
	v_mul_f32_e32 v66, 0xbfb8aa3b, v66
	v_mul_f32_e32 v70, 0xbfb8aa3b, v70
	v_mul_f32_e32 v67, 0xbfb8aa3b, v67
	v_mul_f32_e32 v71, 0xbfb8aa3b, v71
	v_mul_f32_e32 v68, 0xbfb8aa3b, v68
	v_mul_f32_e32 v72, 0xbfb8aa3b, v72
	v_mul_f32_e32 v69, 0xbfb8aa3b, v69
	v_mul_f32_e32 v73, 0xbfb8aa3b, v73
	v_exp_f32_e32 v66, v66
	v_exp_f32_e32 v70, v70
	v_exp_f32_e32 v67, v67
	v_exp_f32_e32 v71, v71
	v_exp_f32_e32 v68, v68
	v_exp_f32_e32 v72, v72
	v_exp_f32_e32 v69, v69
	v_exp_f32_e32 v73, v73
	v_add_f32_e32 v66, 1.0, v66
	v_add_f32_e32 v70, 1.0, v70
	v_add_f32_e32 v67, 1.0, v67
	v_add_f32_e32 v71, 1.0, v71
	v_add_f32_e32 v68, 1.0, v68
	v_add_f32_e32 v72, 1.0, v72
	v_add_f32_e32 v69, 1.0, v69
	v_add_f32_e32 v73, 1.0, v73
	v_rcp_f32_e32 v66, v66
	v_rcp_f32_e32 v70, v70
	v_rcp_f32_e32 v67, v67
	v_rcp_f32_e32 v71, v71
	v_rcp_f32_e32 v68, v68
	v_rcp_f32_e32 v72, v72
	v_rcp_f32_e32 v69, v69
	v_rcp_f32_e32 v73, v73
	v_mul_f32_e32 v66, 0x437f0000, v66
	v_mul_f32_e32 v70, 0x437f0000, v70
	v_mul_f32_e32 v67, 0x437f0000, v67
	v_mul_f32_e32 v71, 0x437f0000, v71
	v_mul_f32_e32 v68, 0x437f0000, v68
	v_mul_f32_e32 v72, 0x437f0000, v72
	v_mul_f32_e32 v69, 0x437f0000, v69
	v_mul_f32_e32 v73, 0x437f0000, v73
	v_rndne_f32_e32 v66, v66
	v_rndne_f32_e32 v70, v70
	v_rndne_f32_e32 v67, v67
	v_rndne_f32_e32 v71, v71
	v_rndne_f32_e32 v68, v68
	v_rndne_f32_e32 v72, v72
	v_rndne_f32_e32 v69, v69
	v_rndne_f32_e32 v73, v73
	v_cvt_u32_f32_e32 v66, v66
	v_cvt_u32_f32_e32 v70, v70
	v_cvt_u32_f32_e32 v67, v67
	v_cvt_u32_f32_e32 v71, v71
	v_cvt_u32_f32_sdwa v68, v68 dst_sel:WORD_1 dst_unused:UNUSED_PAD src0_sel:DWORD
	v_cvt_u32_f32_sdwa v72, v72 dst_sel:WORD_1 dst_unused:UNUSED_PAD src0_sel:DWORD
	v_cvt_u32_f32_sdwa v69, v69 dst_sel:BYTE_3 dst_unused:UNUSED_PAD src0_sel:DWORD
	v_cvt_u32_f32_sdwa v73, v73 dst_sel:BYTE_3 dst_unused:UNUSED_PAD src0_sel:DWORD
	v_lshl_or_b32 v66, v67, 8, v66
	v_lshl_or_b32 v67, v71, 8, v70
	v_or3_b32 v66, v66, v68, v69
	v_or3_b32 v67, v67, v72, v73
	v_lshl_add_u64 v[68:69], v[92:93], 0, v[98:99]
	global_store_dwordx2 v[68:69], v[66:67], off

.LBB0_768:
	s_and_b64 vcc, exec, s[50:51]
	s_cbranch_vccz .LBB0_770
	v_add_u32_e32 v70, s10, v146
	v_ashrrev_i32_e32 v71, 31, v70
	v_add_f32_e32 v58, v98, v228
	v_add_f32_e32 v62, v102, v232
	v_add_f32_e32 v59, v99, v229
	v_add_f32_e32 v63, v103, v233
	v_add_f32_e32 v60, v86, v230
	v_add_f32_e32 v64, v100, v234
	v_add_f32_e32 v61, v87, v231
	v_add_f32_e32 v65, v101, v235
	v_mul_f32_e32 v58, 0xbfb8aa3b, v58
	v_mul_f32_e32 v62, 0xbfb8aa3b, v62
	v_mul_f32_e32 v59, 0xbfb8aa3b, v59
	v_mul_f32_e32 v63, 0xbfb8aa3b, v63
	v_mul_f32_e32 v60, 0xbfb8aa3b, v60
	v_mul_f32_e32 v64, 0xbfb8aa3b, v64
	v_mul_f32_e32 v61, 0xbfb8aa3b, v61
	v_mul_f32_e32 v65, 0xbfb8aa3b, v65
	v_exp_f32_e32 v58, v58
	v_exp_f32_e32 v62, v62
	v_exp_f32_e32 v59, v59
	v_exp_f32_e32 v63, v63
	v_exp_f32_e32 v60, v60
	v_exp_f32_e32 v64, v64
	v_exp_f32_e32 v61, v61
	v_exp_f32_e32 v65, v65
	v_add_f32_e32 v58, 1.0, v58
	v_add_f32_e32 v62, 1.0, v62
	v_add_f32_e32 v59, 1.0, v59
	v_add_f32_e32 v63, 1.0, v63
	v_add_f32_e32 v60, 1.0, v60
	v_add_f32_e32 v64, 1.0, v64
	v_add_f32_e32 v61, 1.0, v61
	v_add_f32_e32 v65, 1.0, v65
	v_rcp_f32_e32 v58, v58
	v_rcp_f32_e32 v62, v62
	v_rcp_f32_e32 v59, v59
	v_rcp_f32_e32 v63, v63
	v_rcp_f32_e32 v60, v60
	v_rcp_f32_e32 v64, v64
	v_rcp_f32_e32 v61, v61
	v_rcp_f32_e32 v65, v65
	v_mul_f32_e32 v58, 0x437f0000, v58
	v_mul_f32_e32 v62, 0x437f0000, v62
	v_mul_f32_e32 v59, 0x437f0000, v59
	v_mul_f32_e32 v63, 0x437f0000, v63
	v_mul_f32_e32 v60, 0x437f0000, v60
	v_mul_f32_e32 v64, 0x437f0000, v64
	v_mul_f32_e32 v61, 0x437f0000, v61
	v_mul_f32_e32 v65, 0x437f0000, v65
	v_rndne_f32_e32 v58, v58
	v_rndne_f32_e32 v62, v62
	v_rndne_f32_e32 v59, v59
	v_rndne_f32_e32 v63, v63
	v_rndne_f32_e32 v60, v60
	v_rndne_f32_e32 v64, v64
	v_rndne_f32_e32 v61, v61
	v_rndne_f32_e32 v65, v65
	v_cvt_u32_f32_e32 v58, v58
	v_cvt_u32_f32_e32 v62, v62
	v_cvt_u32_f32_e32 v59, v59
	v_cvt_u32_f32_e32 v63, v63
	v_cvt_u32_f32_sdwa v60, v60 dst_sel:WORD_1 dst_unused:UNUSED_PAD src0_sel:DWORD
	v_cvt_u32_f32_sdwa v64, v64 dst_sel:WORD_1 dst_unused:UNUSED_PAD src0_sel:DWORD
	v_cvt_u32_f32_sdwa v61, v61 dst_sel:BYTE_3 dst_unused:UNUSED_PAD src0_sel:DWORD
	v_cvt_u32_f32_sdwa v65, v65 dst_sel:BYTE_3 dst_unused:UNUSED_PAD src0_sel:DWORD
	v_lshl_or_b32 v58, v59, 8, v58
	v_lshl_or_b32 v59, v63, 8, v62
	v_or3_b32 v58, v58, v60, v61
	v_or3_b32 v59, v59, v64, v65
	v_lshl_add_u64 v[60:61], v[76:77], 0, v[70:71]
	global_store_dwordx2 v[60:61], v[58:59], off

.LBB0_830:
	s_and_b64 vcc, exec, s[50:51]
	s_cbranch_vccz .LBB0_832
	v_add_u32_e32 v82, s10, v122
	v_ashrrev_i32_e32 v83, 31, v82
	v_add_f32_e32 v50, v60, v236
	v_add_f32_e32 v54, v88, v240
	v_add_f32_e32 v51, v61, v237
	v_add_f32_e32 v55, v89, v241
	v_add_f32_e32 v52, v58, v238
	v_add_f32_e32 v56, v86, v206
	v_add_f32_e32 v53, v59, v239
	v_add_f32_e32 v57, v87, v207
	v_mul_f32_e32 v50, 0xbfb8aa3b, v50
	v_mul_f32_e32 v54, 0xbfb8aa3b, v54
	v_mul_f32_e32 v51, 0xbfb8aa3b, v51
	v_mul_f32_e32 v55, 0xbfb8aa3b, v55
	v_mul_f32_e32 v52, 0xbfb8aa3b, v52
	v_mul_f32_e32 v56, 0xbfb8aa3b, v56
	v_mul_f32_e32 v53, 0xbfb8aa3b, v53
	v_mul_f32_e32 v57, 0xbfb8aa3b, v57
	v_exp_f32_e32 v50, v50
	v_exp_f32_e32 v54, v54
	v_exp_f32_e32 v51, v51
	v_exp_f32_e32 v55, v55
	v_exp_f32_e32 v52, v52
	v_exp_f32_e32 v56, v56
	v_exp_f32_e32 v53, v53
	v_exp_f32_e32 v57, v57
	v_add_f32_e32 v50, 1.0, v50
	v_add_f32_e32 v54, 1.0, v54
	v_add_f32_e32 v51, 1.0, v51
	v_add_f32_e32 v55, 1.0, v55
	v_add_f32_e32 v52, 1.0, v52
	v_add_f32_e32 v56, 1.0, v56
	v_add_f32_e32 v53, 1.0, v53
	v_add_f32_e32 v57, 1.0, v57
	v_rcp_f32_e32 v50, v50
	v_rcp_f32_e32 v54, v54
	v_rcp_f32_e32 v51, v51
	v_rcp_f32_e32 v55, v55
	v_rcp_f32_e32 v52, v52
	v_rcp_f32_e32 v56, v56
	v_rcp_f32_e32 v53, v53
	v_rcp_f32_e32 v57, v57
	v_mul_f32_e32 v50, 0x437f0000, v50
	v_mul_f32_e32 v54, 0x437f0000, v54
	v_mul_f32_e32 v51, 0x437f0000, v51
	v_mul_f32_e32 v55, 0x437f0000, v55
	v_mul_f32_e32 v52, 0x437f0000, v52
	v_mul_f32_e32 v56, 0x437f0000, v56
	v_mul_f32_e32 v53, 0x437f0000, v53
	v_mul_f32_e32 v57, 0x437f0000, v57
	v_rndne_f32_e32 v50, v50
	v_rndne_f32_e32 v54, v54
	v_rndne_f32_e32 v51, v51
	v_rndne_f32_e32 v55, v55
	v_rndne_f32_e32 v52, v52
	v_rndne_f32_e32 v56, v56
	v_rndne_f32_e32 v53, v53
	v_rndne_f32_e32 v57, v57
	v_cvt_u32_f32_e32 v50, v50
	v_cvt_u32_f32_e32 v54, v54
	v_cvt_u32_f32_e32 v51, v51
	v_cvt_u32_f32_e32 v55, v55
	v_cvt_u32_f32_sdwa v52, v52 dst_sel:WORD_1 dst_unused:UNUSED_PAD src0_sel:DWORD
	v_cvt_u32_f32_sdwa v56, v56 dst_sel:WORD_1 dst_unused:UNUSED_PAD src0_sel:DWORD
	v_cvt_u32_f32_sdwa v53, v53 dst_sel:BYTE_3 dst_unused:UNUSED_PAD src0_sel:DWORD
	v_cvt_u32_f32_sdwa v57, v57 dst_sel:BYTE_3 dst_unused:UNUSED_PAD src0_sel:DWORD
	v_lshl_or_b32 v50, v51, 8, v50
	v_lshl_or_b32 v51, v55, 8, v54
	v_or3_b32 v50, v50, v52, v53
	v_or3_b32 v51, v51, v56, v57
	v_lshl_add_u64 v[52:53], v[76:77], 0, v[82:83]
	global_store_dwordx2 v[52:53], v[50:51], off

.LBB0_898:
	s_and_b64 vcc, exec, s[50:51]
	s_cbranch_vccz .LBB0_900
	v_add_u32_e32 v54, s10, v146
	v_ashrrev_i32_e32 v55, 31, v54
	v_add_f32_e32 v42, v82, v228
	v_add_f32_e32 v46, v86, v232
	v_add_f32_e32 v43, v83, v229
	v_add_f32_e32 v47, v87, v233
	v_add_f32_e32 v44, v70, v230
	v_add_f32_e32 v48, v84, v234
	v_add_f32_e32 v45, v71, v231
	v_add_f32_e32 v49, v85, v235
	v_mul_f32_e32 v42, 0xbfb8aa3b, v42
	v_mul_f32_e32 v46, 0xbfb8aa3b, v46
	v_mul_f32_e32 v43, 0xbfb8aa3b, v43
	v_mul_f32_e32 v47, 0xbfb8aa3b, v47
	v_mul_f32_e32 v44, 0xbfb8aa3b, v44
	v_mul_f32_e32 v48, 0xbfb8aa3b, v48
	v_mul_f32_e32 v45, 0xbfb8aa3b, v45
	v_mul_f32_e32 v49, 0xbfb8aa3b, v49
	v_exp_f32_e32 v42, v42
	v_exp_f32_e32 v46, v46
	v_exp_f32_e32 v43, v43
	v_exp_f32_e32 v47, v47
	v_exp_f32_e32 v44, v44
	v_exp_f32_e32 v48, v48
	v_exp_f32_e32 v45, v45
	v_exp_f32_e32 v49, v49
	v_add_f32_e32 v42, 1.0, v42
	v_add_f32_e32 v46, 1.0, v46
	v_add_f32_e32 v43, 1.0, v43
	v_add_f32_e32 v47, 1.0, v47
	v_add_f32_e32 v44, 1.0, v44
	v_add_f32_e32 v48, 1.0, v48
	v_add_f32_e32 v45, 1.0, v45
	v_add_f32_e32 v49, 1.0, v49
	v_rcp_f32_e32 v42, v42
	v_rcp_f32_e32 v46, v46
	v_rcp_f32_e32 v43, v43
	v_rcp_f32_e32 v47, v47
	v_rcp_f32_e32 v44, v44
	v_rcp_f32_e32 v48, v48
	v_rcp_f32_e32 v45, v45
	v_rcp_f32_e32 v49, v49
	v_mul_f32_e32 v42, 0x437f0000, v42
	v_mul_f32_e32 v46, 0x437f0000, v46
	v_mul_f32_e32 v43, 0x437f0000, v43
	v_mul_f32_e32 v47, 0x437f0000, v47
	v_mul_f32_e32 v44, 0x437f0000, v44
	v_mul_f32_e32 v48, 0x437f0000, v48
	v_mul_f32_e32 v45, 0x437f0000, v45
	v_mul_f32_e32 v49, 0x437f0000, v49
	v_rndne_f32_e32 v42, v42
	v_rndne_f32_e32 v46, v46
	v_rndne_f32_e32 v43, v43
	v_rndne_f32_e32 v47, v47
	v_rndne_f32_e32 v44, v44
	v_rndne_f32_e32 v48, v48
	v_rndne_f32_e32 v45, v45
	v_rndne_f32_e32 v49, v49
	v_cvt_u32_f32_e32 v42, v42
	v_cvt_u32_f32_e32 v46, v46
	v_cvt_u32_f32_e32 v43, v43
	v_cvt_u32_f32_e32 v47, v47
	v_cvt_u32_f32_sdwa v44, v44 dst_sel:WORD_1 dst_unused:UNUSED_PAD src0_sel:DWORD
	v_cvt_u32_f32_sdwa v48, v48 dst_sel:WORD_1 dst_unused:UNUSED_PAD src0_sel:DWORD
	v_cvt_u32_f32_sdwa v45, v45 dst_sel:BYTE_3 dst_unused:UNUSED_PAD src0_sel:DWORD
	v_cvt_u32_f32_sdwa v49, v49 dst_sel:BYTE_3 dst_unused:UNUSED_PAD src0_sel:DWORD
	v_lshl_or_b32 v42, v43, 8, v42
	v_lshl_or_b32 v43, v47, 8, v46
	v_or3_b32 v42, v42, v44, v45
	v_or3_b32 v43, v43, v48, v49
	v_lshl_add_u64 v[44:45], v[60:61], 0, v[54:55]
	global_store_dwordx2 v[44:45], v[42:43], off

.LBB0_960:
	s_and_b64 vcc, exec, s[50:51]
	s_cbranch_vccz .LBB0_962
	v_add_u32_e32 v66, s10, v122
	v_ashrrev_i32_e32 v67, 31, v66
	v_add_f32_e32 v34, v44, v236
	v_add_f32_e32 v38, v72, v240
	v_add_f32_e32 v35, v45, v237
	v_add_f32_e32 v39, v73, v241
	v_add_f32_e32 v36, v42, v238
	v_add_f32_e32 v40, v70, v206
	v_add_f32_e32 v37, v43, v239
	v_add_f32_e32 v41, v71, v207
	v_mul_f32_e32 v34, 0xbfb8aa3b, v34
	v_mul_f32_e32 v38, 0xbfb8aa3b, v38
	v_mul_f32_e32 v35, 0xbfb8aa3b, v35
	v_mul_f32_e32 v39, 0xbfb8aa3b, v39
	v_mul_f32_e32 v36, 0xbfb8aa3b, v36
	v_mul_f32_e32 v40, 0xbfb8aa3b, v40
	v_mul_f32_e32 v37, 0xbfb8aa3b, v37
	v_mul_f32_e32 v41, 0xbfb8aa3b, v41
	v_exp_f32_e32 v34, v34
	v_exp_f32_e32 v38, v38
	v_exp_f32_e32 v35, v35
	v_exp_f32_e32 v39, v39
	v_exp_f32_e32 v36, v36
	v_exp_f32_e32 v40, v40
	v_exp_f32_e32 v37, v37
	v_exp_f32_e32 v41, v41
	v_add_f32_e32 v34, 1.0, v34
	v_add_f32_e32 v38, 1.0, v38
	v_add_f32_e32 v35, 1.0, v35
	v_add_f32_e32 v39, 1.0, v39
	v_add_f32_e32 v36, 1.0, v36
	v_add_f32_e32 v40, 1.0, v40
	v_add_f32_e32 v37, 1.0, v37
	v_add_f32_e32 v41, 1.0, v41
	v_rcp_f32_e32 v34, v34
	v_rcp_f32_e32 v38, v38
	v_rcp_f32_e32 v35, v35
	v_rcp_f32_e32 v39, v39
	v_rcp_f32_e32 v36, v36
	v_rcp_f32_e32 v40, v40
	v_rcp_f32_e32 v37, v37
	v_rcp_f32_e32 v41, v41
	v_mul_f32_e32 v34, 0x437f0000, v34
	v_mul_f32_e32 v38, 0x437f0000, v38
	v_mul_f32_e32 v35, 0x437f0000, v35
	v_mul_f32_e32 v39, 0x437f0000, v39
	v_mul_f32_e32 v36, 0x437f0000, v36
	v_mul_f32_e32 v40, 0x437f0000, v40
	v_mul_f32_e32 v37, 0x437f0000, v37
	v_mul_f32_e32 v41, 0x437f0000, v41
	v_rndne_f32_e32 v34, v34
	v_rndne_f32_e32 v38, v38
	v_rndne_f32_e32 v35, v35
	v_rndne_f32_e32 v39, v39
	v_rndne_f32_e32 v36, v36
	v_rndne_f32_e32 v40, v40
	v_rndne_f32_e32 v37, v37
	v_rndne_f32_e32 v41, v41
	v_cvt_u32_f32_e32 v34, v34
	v_cvt_u32_f32_e32 v38, v38
	v_cvt_u32_f32_e32 v35, v35
	v_cvt_u32_f32_e32 v39, v39
	v_cvt_u32_f32_sdwa v36, v36 dst_sel:WORD_1 dst_unused:UNUSED_PAD src0_sel:DWORD
	v_cvt_u32_f32_sdwa v40, v40 dst_sel:WORD_1 dst_unused:UNUSED_PAD src0_sel:DWORD
	v_cvt_u32_f32_sdwa v37, v37 dst_sel:BYTE_3 dst_unused:UNUSED_PAD src0_sel:DWORD
	v_cvt_u32_f32_sdwa v41, v41 dst_sel:BYTE_3 dst_unused:UNUSED_PAD src0_sel:DWORD
	v_lshl_or_b32 v34, v35, 8, v34
	v_lshl_or_b32 v35, v39, 8, v38
	v_or3_b32 v34, v34, v36, v37
	v_or3_b32 v35, v35, v40, v41
	v_lshl_add_u64 v[36:37], v[60:61], 0, v[66:67]
	global_store_dwordx2 v[36:37], v[34:35], off

.LBB0_1028:
	s_and_b64 vcc, exec, s[50:51]
	s_cbranch_vccz .LBB0_1030
	v_add_u32_e32 v38, s10, v146
	v_ashrrev_i32_e32 v39, 31, v38
	v_add_f32_e32 v26, v66, v228
	v_add_f32_e32 v30, v70, v232
	v_add_f32_e32 v27, v67, v229
	v_add_f32_e32 v31, v71, v233
	v_add_f32_e32 v28, v54, v230
	v_add_f32_e32 v32, v68, v234
	v_add_f32_e32 v29, v55, v231
	v_add_f32_e32 v33, v69, v235
	v_mul_f32_e32 v26, 0xbfb8aa3b, v26
	v_mul_f32_e32 v30, 0xbfb8aa3b, v30
	v_mul_f32_e32 v27, 0xbfb8aa3b, v27
	v_mul_f32_e32 v31, 0xbfb8aa3b, v31
	v_mul_f32_e32 v28, 0xbfb8aa3b, v28
	v_mul_f32_e32 v32, 0xbfb8aa3b, v32
	v_mul_f32_e32 v29, 0xbfb8aa3b, v29
	v_mul_f32_e32 v33, 0xbfb8aa3b, v33
	v_exp_f32_e32 v26, v26
	v_exp_f32_e32 v30, v30
	v_exp_f32_e32 v27, v27
	v_exp_f32_e32 v31, v31
	v_exp_f32_e32 v28, v28
	v_exp_f32_e32 v32, v32
	v_exp_f32_e32 v29, v29
	v_exp_f32_e32 v33, v33
	v_add_f32_e32 v26, 1.0, v26
	v_add_f32_e32 v30, 1.0, v30
	v_add_f32_e32 v27, 1.0, v27
	v_add_f32_e32 v31, 1.0, v31
	v_add_f32_e32 v28, 1.0, v28
	v_add_f32_e32 v32, 1.0, v32
	v_add_f32_e32 v29, 1.0, v29
	v_add_f32_e32 v33, 1.0, v33
	v_rcp_f32_e32 v26, v26
	v_rcp_f32_e32 v30, v30
	v_rcp_f32_e32 v27, v27
	v_rcp_f32_e32 v31, v31
	v_rcp_f32_e32 v28, v28
	v_rcp_f32_e32 v32, v32
	v_rcp_f32_e32 v29, v29
	v_rcp_f32_e32 v33, v33
	v_mul_f32_e32 v26, 0x437f0000, v26
	v_mul_f32_e32 v30, 0x437f0000, v30
	v_mul_f32_e32 v27, 0x437f0000, v27
	v_mul_f32_e32 v31, 0x437f0000, v31
	v_mul_f32_e32 v28, 0x437f0000, v28
	v_mul_f32_e32 v32, 0x437f0000, v32
	v_mul_f32_e32 v29, 0x437f0000, v29
	v_mul_f32_e32 v33, 0x437f0000, v33
	v_rndne_f32_e32 v26, v26
	v_rndne_f32_e32 v30, v30
	v_rndne_f32_e32 v27, v27
	v_rndne_f32_e32 v31, v31
	v_rndne_f32_e32 v28, v28
	v_rndne_f32_e32 v32, v32
	v_rndne_f32_e32 v29, v29
	v_rndne_f32_e32 v33, v33
	v_cvt_u32_f32_e32 v26, v26
	v_cvt_u32_f32_e32 v30, v30
	v_cvt_u32_f32_e32 v27, v27
	v_cvt_u32_f32_e32 v31, v31
	v_cvt_u32_f32_sdwa v28, v28 dst_sel:WORD_1 dst_unused:UNUSED_PAD src0_sel:DWORD
	v_cvt_u32_f32_sdwa v32, v32 dst_sel:WORD_1 dst_unused:UNUSED_PAD src0_sel:DWORD
	v_cvt_u32_f32_sdwa v29, v29 dst_sel:BYTE_3 dst_unused:UNUSED_PAD src0_sel:DWORD
	v_cvt_u32_f32_sdwa v33, v33 dst_sel:BYTE_3 dst_unused:UNUSED_PAD src0_sel:DWORD
	v_lshl_or_b32 v26, v27, 8, v26
	v_lshl_or_b32 v27, v31, 8, v30
	v_or3_b32 v26, v26, v28, v29
	v_or3_b32 v27, v27, v32, v33
	v_lshl_add_u64 v[28:29], v[44:45], 0, v[38:39]
	global_store_dwordx2 v[28:29], v[26:27], off

.LBB0_1090:
	s_and_b64 vcc, exec, s[50:51]
	s_cbranch_vccz .LBB0_1092
	v_add_u32_e32 v50, s10, v122
	v_ashrrev_i32_e32 v51, 31, v50
	v_add_f32_e32 v18, v28, v236
	v_add_f32_e32 v22, v56, v240
	v_add_f32_e32 v19, v29, v237
	v_add_f32_e32 v23, v57, v241
	v_add_f32_e32 v20, v26, v238
	v_add_f32_e32 v24, v54, v206
	v_add_f32_e32 v21, v27, v239
	v_add_f32_e32 v25, v55, v207
	v_mul_f32_e32 v18, 0xbfb8aa3b, v18
	v_mul_f32_e32 v22, 0xbfb8aa3b, v22
	v_mul_f32_e32 v19, 0xbfb8aa3b, v19
	v_mul_f32_e32 v23, 0xbfb8aa3b, v23
	v_mul_f32_e32 v20, 0xbfb8aa3b, v20
	v_mul_f32_e32 v24, 0xbfb8aa3b, v24
	v_mul_f32_e32 v21, 0xbfb8aa3b, v21
	v_mul_f32_e32 v25, 0xbfb8aa3b, v25
	v_exp_f32_e32 v18, v18
	v_exp_f32_e32 v22, v22
	v_exp_f32_e32 v19, v19
	v_exp_f32_e32 v23, v23
	v_exp_f32_e32 v20, v20
	v_exp_f32_e32 v24, v24
	v_exp_f32_e32 v21, v21
	v_exp_f32_e32 v25, v25
	v_add_f32_e32 v18, 1.0, v18
	v_add_f32_e32 v22, 1.0, v22
	v_add_f32_e32 v19, 1.0, v19
	v_add_f32_e32 v23, 1.0, v23
	v_add_f32_e32 v20, 1.0, v20
	v_add_f32_e32 v24, 1.0, v24
	v_add_f32_e32 v21, 1.0, v21
	v_add_f32_e32 v25, 1.0, v25
	v_rcp_f32_e32 v18, v18
	v_rcp_f32_e32 v22, v22
	v_rcp_f32_e32 v19, v19
	v_rcp_f32_e32 v23, v23
	v_rcp_f32_e32 v20, v20
	v_rcp_f32_e32 v24, v24
	v_rcp_f32_e32 v21, v21
	v_rcp_f32_e32 v25, v25
	v_mul_f32_e32 v18, 0x437f0000, v18
	v_mul_f32_e32 v22, 0x437f0000, v22
	v_mul_f32_e32 v19, 0x437f0000, v19
	v_mul_f32_e32 v23, 0x437f0000, v23
	v_mul_f32_e32 v20, 0x437f0000, v20
	v_mul_f32_e32 v24, 0x437f0000, v24
	v_mul_f32_e32 v21, 0x437f0000, v21
	v_mul_f32_e32 v25, 0x437f0000, v25
	v_rndne_f32_e32 v18, v18
	v_rndne_f32_e32 v22, v22
	v_rndne_f32_e32 v19, v19
	v_rndne_f32_e32 v23, v23
	v_rndne_f32_e32 v20, v20
	v_rndne_f32_e32 v24, v24
	v_rndne_f32_e32 v21, v21
	v_rndne_f32_e32 v25, v25
	v_cvt_u32_f32_e32 v18, v18
	v_cvt_u32_f32_e32 v22, v22
	v_cvt_u32_f32_e32 v19, v19
	v_cvt_u32_f32_e32 v23, v23
	v_cvt_u32_f32_sdwa v20, v20 dst_sel:WORD_1 dst_unused:UNUSED_PAD src0_sel:DWORD
	v_cvt_u32_f32_sdwa v24, v24 dst_sel:WORD_1 dst_unused:UNUSED_PAD src0_sel:DWORD
	v_cvt_u32_f32_sdwa v21, v21 dst_sel:BYTE_3 dst_unused:UNUSED_PAD src0_sel:DWORD
	v_cvt_u32_f32_sdwa v25, v25 dst_sel:BYTE_3 dst_unused:UNUSED_PAD src0_sel:DWORD
	v_lshl_or_b32 v18, v19, 8, v18
	v_lshl_or_b32 v19, v23, 8, v22
	v_or3_b32 v18, v18, v20, v21
	v_or3_b32 v19, v19, v24, v25
	v_lshl_add_u64 v[20:21], v[44:45], 0, v[50:51]
	global_store_dwordx2 v[20:21], v[18:19], off

.LBB0_1158:
	s_and_b64 vcc, exec, s[28:29]
	s_cbranch_vccz .LBB0_1160
	v_add_u32_e32 v22, s10, v146
	v_ashrrev_i32_e32 v23, 31, v22
	v_add_f32_e32 v10, v50, v228
	v_add_f32_e32 v14, v54, v232
	v_add_f32_e32 v11, v51, v229
	v_add_f32_e32 v15, v55, v233
	v_add_f32_e32 v12, v38, v230
	v_add_f32_e32 v16, v52, v234
	v_add_f32_e32 v13, v39, v231
	v_add_f32_e32 v17, v53, v235
	v_mul_f32_e32 v10, 0xbfb8aa3b, v10
	v_mul_f32_e32 v14, 0xbfb8aa3b, v14
	v_mul_f32_e32 v11, 0xbfb8aa3b, v11
	v_mul_f32_e32 v15, 0xbfb8aa3b, v15
	v_mul_f32_e32 v12, 0xbfb8aa3b, v12
	v_mul_f32_e32 v16, 0xbfb8aa3b, v16
	v_mul_f32_e32 v13, 0xbfb8aa3b, v13
	v_mul_f32_e32 v17, 0xbfb8aa3b, v17
	v_exp_f32_e32 v10, v10
	v_exp_f32_e32 v14, v14
	v_exp_f32_e32 v11, v11
	v_exp_f32_e32 v15, v15
	v_exp_f32_e32 v12, v12
	v_exp_f32_e32 v16, v16
	v_exp_f32_e32 v13, v13
	v_exp_f32_e32 v17, v17
	v_add_f32_e32 v10, 1.0, v10
	v_add_f32_e32 v14, 1.0, v14
	v_add_f32_e32 v11, 1.0, v11
	v_add_f32_e32 v15, 1.0, v15
	v_add_f32_e32 v12, 1.0, v12
	v_add_f32_e32 v16, 1.0, v16
	v_add_f32_e32 v13, 1.0, v13
	v_add_f32_e32 v17, 1.0, v17
	v_rcp_f32_e32 v10, v10
	v_rcp_f32_e32 v14, v14
	v_rcp_f32_e32 v11, v11
	v_rcp_f32_e32 v15, v15
	v_rcp_f32_e32 v12, v12
	v_rcp_f32_e32 v16, v16
	v_rcp_f32_e32 v13, v13
	v_rcp_f32_e32 v17, v17
	v_mul_f32_e32 v10, 0x437f0000, v10
	v_mul_f32_e32 v14, 0x437f0000, v14
	v_mul_f32_e32 v11, 0x437f0000, v11
	v_mul_f32_e32 v15, 0x437f0000, v15
	v_mul_f32_e32 v12, 0x437f0000, v12
	v_mul_f32_e32 v16, 0x437f0000, v16
	v_mul_f32_e32 v13, 0x437f0000, v13
	v_mul_f32_e32 v17, 0x437f0000, v17
	v_rndne_f32_e32 v10, v10
	v_rndne_f32_e32 v14, v14
	v_rndne_f32_e32 v11, v11
	v_rndne_f32_e32 v15, v15
	v_rndne_f32_e32 v12, v12
	v_rndne_f32_e32 v16, v16
	v_rndne_f32_e32 v13, v13
	v_rndne_f32_e32 v17, v17
	v_cvt_u32_f32_e32 v10, v10
	v_cvt_u32_f32_e32 v14, v14
	v_cvt_u32_f32_e32 v11, v11
	v_cvt_u32_f32_e32 v15, v15
	v_cvt_u32_f32_sdwa v12, v12 dst_sel:WORD_1 dst_unused:UNUSED_PAD src0_sel:DWORD
	v_cvt_u32_f32_sdwa v16, v16 dst_sel:WORD_1 dst_unused:UNUSED_PAD src0_sel:DWORD
	v_cvt_u32_f32_sdwa v13, v13 dst_sel:BYTE_3 dst_unused:UNUSED_PAD src0_sel:DWORD
	v_cvt_u32_f32_sdwa v17, v17 dst_sel:BYTE_3 dst_unused:UNUSED_PAD src0_sel:DWORD
	v_lshl_or_b32 v10, v11, 8, v10
	v_lshl_or_b32 v11, v15, 8, v14
	v_or3_b32 v10, v10, v12, v13
	v_or3_b32 v11, v11, v16, v17
	v_lshl_add_u64 v[12:13], v[28:29], 0, v[22:23]
	global_store_dwordx2 v[12:13], v[10:11], off

.LBB0_1221:
	s_and_b64 vcc, exec, s[20:21]
	s_cbranch_vccz .LBB0_1223
	v_add_u32_e32 v34, s10, v122
	v_ashrrev_i32_e32 v35, 31, v34
	v_add_f32_e32 v2, v12, v236
	v_add_f32_e32 v6, v40, v240
	v_add_f32_e32 v3, v13, v237
	v_add_f32_e32 v7, v41, v241
	v_add_f32_e32 v4, v10, v238
	v_add_f32_e32 v8, v38, v206
	v_add_f32_e32 v5, v11, v239
	v_add_f32_e32 v9, v39, v207
	v_mul_f32_e32 v2, 0xbfb8aa3b, v2
	v_mul_f32_e32 v6, 0xbfb8aa3b, v6
	v_mul_f32_e32 v3, 0xbfb8aa3b, v3
	v_mul_f32_e32 v7, 0xbfb8aa3b, v7
	v_mul_f32_e32 v4, 0xbfb8aa3b, v4
	v_mul_f32_e32 v8, 0xbfb8aa3b, v8
	v_mul_f32_e32 v5, 0xbfb8aa3b, v5
	v_mul_f32_e32 v9, 0xbfb8aa3b, v9
	v_exp_f32_e32 v2, v2
	v_exp_f32_e32 v6, v6
	v_exp_f32_e32 v3, v3
	v_exp_f32_e32 v7, v7
	v_exp_f32_e32 v4, v4
	v_exp_f32_e32 v8, v8
	v_exp_f32_e32 v5, v5
	v_exp_f32_e32 v9, v9
	v_add_f32_e32 v2, 1.0, v2
	v_add_f32_e32 v6, 1.0, v6
	v_add_f32_e32 v3, 1.0, v3
	v_add_f32_e32 v7, 1.0, v7
	v_add_f32_e32 v4, 1.0, v4
	v_add_f32_e32 v8, 1.0, v8
	v_add_f32_e32 v5, 1.0, v5
	v_add_f32_e32 v9, 1.0, v9
	v_rcp_f32_e32 v2, v2
	v_rcp_f32_e32 v6, v6
	v_rcp_f32_e32 v3, v3
	v_rcp_f32_e32 v7, v7
	v_rcp_f32_e32 v4, v4
	v_rcp_f32_e32 v8, v8
	v_rcp_f32_e32 v5, v5
	v_rcp_f32_e32 v9, v9
	v_mul_f32_e32 v2, 0x437f0000, v2
	v_mul_f32_e32 v6, 0x437f0000, v6
	v_mul_f32_e32 v3, 0x437f0000, v3
	v_mul_f32_e32 v7, 0x437f0000, v7
	v_mul_f32_e32 v4, 0x437f0000, v4
	v_mul_f32_e32 v8, 0x437f0000, v8
	v_mul_f32_e32 v5, 0x437f0000, v5
	v_mul_f32_e32 v9, 0x437f0000, v9
	v_rndne_f32_e32 v2, v2
	v_rndne_f32_e32 v6, v6
	v_rndne_f32_e32 v3, v3
	v_rndne_f32_e32 v7, v7
	v_rndne_f32_e32 v4, v4
	v_rndne_f32_e32 v8, v8
	v_rndne_f32_e32 v5, v5
	v_rndne_f32_e32 v9, v9
	v_cvt_u32_f32_e32 v2, v2
	v_cvt_u32_f32_e32 v6, v6
	v_cvt_u32_f32_e32 v3, v3
	v_cvt_u32_f32_e32 v7, v7
	v_cvt_u32_f32_sdwa v4, v4 dst_sel:WORD_1 dst_unused:UNUSED_PAD src0_sel:DWORD
	v_cvt_u32_f32_sdwa v8, v8 dst_sel:WORD_1 dst_unused:UNUSED_PAD src0_sel:DWORD
	v_cvt_u32_f32_sdwa v5, v5 dst_sel:BYTE_3 dst_unused:UNUSED_PAD src0_sel:DWORD
	v_cvt_u32_f32_sdwa v9, v9 dst_sel:BYTE_3 dst_unused:UNUSED_PAD src0_sel:DWORD
	v_lshl_or_b32 v2, v3, 8, v2
	v_lshl_or_b32 v3, v7, 8, v6
	v_or3_b32 v2, v2, v4, v5
	v_or3_b32 v3, v3, v8, v9
	v_lshl_add_u64 v[4:5], v[28:29], 0, v[34:35]
	global_store_dwordx2 v[4:5], v[2:3], off
